# a0post + non-temporal (nt) hint on the 64 streaming loads of the P6 scan sweeps
# speedup vs baseline: 1.0049x; 1.0049x over previous
; #define P6F_LOAD(W, g_) _Pragma("unroll") for (int s_ = 0; s_ < 8; ++s_) { const size_t tf_ = (size_t)(t0 + 8 * (g_) + s_); W[s_][0] = *(const unsigned*)(gp + tf_ * NG); W[s_][1] = *(const unsigned*)(gp + tf_ * NG + 256); }
; __global__ void __launch_bounds__(NWAVES * 64, 2) fwd(Args args) {
;     ...
;                 { unsigned wn[8][2], wc_[8][2];
;     ...
;                   P6F_LOAD(wn, 0);
; #pragma unroll 1
;                   for (int g8 = 0; g8 < CHUNK / 8; ++g8) {
; #pragma unroll
;                     for (int s_ = 0; s_ < 8; ++s_) { wc_[s_][0] = wn[s_][0]; wc_[s_][1] = wn[s_][1]; }
;                     if (g8 + 1 < CHUNK / 8) { P6F_LOAD(wn, g8 + 1); }
.LBB0_556:
	s_or_b64 exec, exec, s[34:35]
	v_ashrrev_i32_e32 v22, 8, v16
	v_lshlrev_b32_e32 v20, 7, v26
	v_ashrrev_i32_e32 v23, 31, v22
	v_lshlrev_b64 v[22:23], 11, v[22:23]
	v_ashrrev_i32_e32 v21, 31, v20
	v_lshl_add_u64 v[22:23], v[14:15], 0, v[22:23]
	v_lshlrev_b64 v[26:27], 15, v[20:21]
	v_lshl_add_u64 v[26:27], v[22:23], 0, v[26:27]
	global_load_dword v40, v[26:27], off nt
	global_load_dword v39, v[26:27], off offset:512 nt
	v_or_b32_e32 v26, 1, v20
	v_ashrrev_i32_e32 v27, 31, v26
	v_lshlrev_b64 v[26:27], 15, v[26:27]
	v_lshl_add_u64 v[26:27], v[22:23], 0, v[26:27]
	global_load_dword v38, v[26:27], off nt
	global_load_dword v36, v[26:27], off offset:512 nt
	v_or_b32_e32 v26, 2, v20
	v_ashrrev_i32_e32 v27, 31, v26
	v_lshlrev_b64 v[26:27], 15, v[26:27]
	v_and_b32_e32 v2, 0xc00, v33
	v_lshl_add_u64 v[26:27], v[22:23], 0, v[26:27]
	v_add_u32_e32 v28, v32, v2
	global_load_dword v37, v[26:27], off nt
	global_load_dword v2, v[26:27], off offset:512 nt
	v_or_b32_e32 v26, 3, v20
	v_ashrrev_i32_e32 v27, 31, v26
	v_lshlrev_b64 v[26:27], 15, v[26:27]
	v_lshl_add_u64 v[26:27], v[22:23], 0, v[26:27]
	global_load_dword v41, v[26:27], off nt
	global_load_dword v43, v[26:27], off offset:512 nt
	v_or_b32_e32 v26, 4, v20
	v_ashrrev_i32_e32 v27, 31, v26
	v_lshlrev_b64 v[26:27], 15, v[26:27]
	v_lshl_add_u64 v[26:27], v[22:23], 0, v[26:27]
	global_load_dword v45, v[26:27], off nt
	global_load_dword v46, v[26:27], off offset:512 nt
	v_or_b32_e32 v26, 5, v20
	v_ashrrev_i32_e32 v27, 31, v26
	v_lshlrev_b64 v[26:27], 15, v[26:27]
	v_lshl_add_u64 v[26:27], v[22:23], 0, v[26:27]
	global_load_dword v47, v[26:27], off nt
	global_load_dword v48, v[26:27], off offset:512 nt
	v_or_b32_e32 v26, 6, v20
	v_ashrrev_i32_e32 v27, 31, v26
	v_lshlrev_b64 v[26:27], 15, v[26:27]
	v_lshl_add_u64 v[26:27], v[22:23], 0, v[26:27]
	global_load_dword v51, v[26:27], off nt
	global_load_dword v52, v[26:27], off offset:512 nt
	v_or_b32_e32 v26, 7, v20
	v_ashrrev_i32_e32 v27, 31, v26
	v_lshlrev_b64 v[26:27], 15, v[26:27]
	v_lshl_add_u64 v[26:27], v[22:23], 0, v[26:27]
	global_load_dword v55, v[26:27], off nt
	global_load_dword v56, v[26:27], off offset:512 nt
	v_ashrrev_i32_e32 v29, 31, v28
	v_lshlrev_b64 v[26:27], 13, v[20:21]
	v_lshl_add_u64 v[26:27], v[28:29], 1, v[26:27]
	v_lshl_add_u64 v[28:29], v[10:11], 0, v[26:27]
	s_mov_b32 s9, 0
	s_waitcnt vmcnt(15)
	v_mov_b32_e32 v21, v40
	s_waitcnt vmcnt(14)
	v_mov_b32_e32 v44, v39
	s_waitcnt vmcnt(13)
	v_mov_b32_e32 v49, v38
	s_waitcnt vmcnt(12)
	v_mov_b32_e32 v50, v36
	s_waitcnt vmcnt(11)
	v_mov_b32_e32 v53, v37
	s_waitcnt vmcnt(10)
	v_mov_b32_e32 v54, v2
	s_waitcnt vmcnt(9)
	v_mov_b32_e32 v57, v41
	s_waitcnt vmcnt(8)
	v_mov_b32_e32 v58, v43
	s_waitcnt vmcnt(7)
	v_mov_b32_e32 v59, v45
	s_waitcnt vmcnt(6)
	v_mov_b32_e32 v60, v46
	s_waitcnt vmcnt(5)
	v_mov_b32_e32 v61, v47
	s_waitcnt vmcnt(4)
	v_mov_b32_e32 v62, v48
	s_waitcnt vmcnt(3)
	v_mov_b32_e32 v63, v51
	s_waitcnt vmcnt(2)
	v_mov_b32_e32 v64, v52
	s_waitcnt vmcnt(1)
	v_mov_b32_e32 v65, v55
	s_waitcnt vmcnt(0)
	v_mov_b32_e32 v66, v56
	s_branch .LBB0_558

; #define P6F_LOAD(W, g_) _Pragma("unroll") for (int s_ = 0; s_ < 8; ++s_) { const size_t tf_ = (size_t)(t0 + 8 * (g_) + s_); W[s_][0] = *(const unsigned*)(gp + tf_ * NG); W[s_][1] = *(const unsigned*)(gp + tf_ * NG + 256); }
; #define P6R_LOAD(W, g_) _Pragma("unroll") for (int s_ = 0; s_ < 4; ++s_) { const size_t tr_ = (size_t)(t0 + CHUNK - 1 - 4 * (g_) - s_); W[s_][0] = *(const unsigned*)(gp + tr_ * NG + 512); W[s_][1] = *(const unsigned*)(gp + tr_ * NG + 768); \
;                     W[s_][2] = *(const unsigned*)(yp + tr_ * NZ); W[s_][3] = *(const unsigned*)(ap + tr_ * D); }
; __global__ void __launch_bounds__(NWAVES * 64, 2) fwd(Args args) {
;     ...
;                   for (int g8 = 0; g8 < CHUNK / 8; ++g8) {
; #pragma unroll
;                     for (int s_ = 0; s_ < 8; ++s_) { wc_[s_][0] = wn[s_][0]; wc_[s_][1] = wn[s_][1]; }
;                     if (g8 + 1 < CHUNK / 8) { P6F_LOAD(wn, g8 + 1); }
;     ...
;                 { unsigned wn[4][4], wc_[4][4];
;     ...
;                   P6R_LOAD(wn, 0);
.LBB0_558:
	s_cmpk_lg_i32 s9, 0x78
	s_cbranch_scc0 .LBB0_557
	v_add_u32_e32 v66, s9, v20
	v_add_u32_e32 v58, 8, v66
	v_ashrrev_i32_e32 v59, 31, v58
	v_lshlrev_b64 v[58:59], 15, v[58:59]
	v_lshl_add_u64 v[58:59], v[22:23], 0, v[58:59]
	global_load_dword v21, v[58:59], off nt
	global_load_dword v44, v[58:59], off offset:512 nt
	v_add_u32_e32 v58, 9, v66
	v_ashrrev_i32_e32 v59, 31, v58
	v_lshlrev_b64 v[58:59], 15, v[58:59]
	v_lshl_add_u64 v[58:59], v[22:23], 0, v[58:59]
	global_load_dword v49, v[58:59], off nt
	global_load_dword v50, v[58:59], off offset:512 nt
	v_add_u32_e32 v58, 10, v66
	v_ashrrev_i32_e32 v59, 31, v58
	v_lshlrev_b64 v[58:59], 15, v[58:59]
	v_lshl_add_u64 v[58:59], v[22:23], 0, v[58:59]
	global_load_dword v53, v[58:59], off nt
	global_load_dword v54, v[58:59], off offset:512 nt
	v_add_u32_e32 v58, 11, v66
	v_add_u32_e32 v60, 12, v66
	v_add_u32_e32 v62, 13, v66
	v_add_u32_e32 v64, 14, v66
	v_add_u32_e32 v66, 15, v66
	v_ashrrev_i32_e32 v59, 31, v58
	v_ashrrev_i32_e32 v61, 31, v60
	v_ashrrev_i32_e32 v63, 31, v62
	v_ashrrev_i32_e32 v65, 31, v64
	v_ashrrev_i32_e32 v67, 31, v66
	v_lshlrev_b64 v[58:59], 15, v[58:59]
	v_lshlrev_b64 v[60:61], 15, v[60:61]
	v_lshlrev_b64 v[62:63], 15, v[62:63]
	v_lshlrev_b64 v[64:65], 15, v[64:65]
	v_lshlrev_b64 v[66:67], 15, v[66:67]
	v_lshl_add_u64 v[58:59], v[22:23], 0, v[58:59]
	v_lshl_add_u64 v[60:61], v[22:23], 0, v[60:61]
	v_lshl_add_u64 v[62:63], v[22:23], 0, v[62:63]
	v_lshl_add_u64 v[64:65], v[22:23], 0, v[64:65]
	v_lshl_add_u64 v[66:67], v[22:23], 0, v[66:67]
	global_load_dword v57, v[58:59], off nt
	s_nop 0
	global_load_dword v58, v[58:59], off offset:512 nt
	s_nop 0
	global_load_dword v59, v[60:61], off nt
	s_nop 0
	global_load_dword v60, v[60:61], off offset:512 nt
	s_nop 0
	global_load_dword v61, v[62:63], off nt
	s_nop 0
	global_load_dword v62, v[62:63], off offset:512 nt
	s_nop 0
	global_load_dword v63, v[64:65], off nt
	s_nop 0
	global_load_dword v64, v[64:65], off offset:512 nt
	s_nop 0
	global_load_dword v65, v[66:67], off nt
	s_nop 0
	global_load_dword v66, v[66:67], off offset:512 nt
	s_branch .LBB0_557
.LBB0_560:
	v_or_b32_e32 v36, 0x7f, v20
	v_ashrrev_i32_e32 v37, 31, v36
	v_lshlrev_b64 v[24:25], 1, v[16:17]
	v_lshlrev_b64 v[28:29], 15, v[36:37]
	v_lshl_add_u64 v[16:17], v[8:9], 0, v[24:25]
	v_lshl_add_u64 v[28:29], v[22:23], 0, v[28:29]
	v_lshl_add_u64 v[24:25], v[6:7], 0, v[24:25]
	global_load_dword v2, v[28:29], off offset:1024 nt
	global_load_dword v21, v[28:29], off offset:1536 nt
	v_mad_i64_i32 v[28:29], s[34:35], v36, s25, v[16:17]
	v_lshlrev_b64 v[36:37], 13, v[36:37]
	v_or_b32_e32 v40, 0x7e, v20
	v_lshl_add_u64 v[36:37], v[24:25], 0, v[36:37]
	v_ashrrev_i32_e32 v41, 31, v40
	global_load_dword v28, v[28:29], off nt
	v_or_b32_e32 v46, 0x7d, v20
	global_load_dword v29, v[36:37], off nt
	v_lshlrev_b64 v[36:37], 15, v[40:41]
	v_lshl_add_u64 v[38:39], v[22:23], 0, v[36:37]
	v_ashrrev_i32_e32 v47, 31, v46
	global_load_dword v36, v[38:39], off offset:1024 nt
	global_load_dword v37, v[38:39], off offset:1536 nt
	v_mad_i64_i32 v[38:39], s[34:35], v40, s25, v[16:17]
	v_lshlrev_b64 v[40:41], 13, v[40:41]
	v_lshlrev_b64 v[44:45], 15, v[46:47]
	v_or_b32_e32 v52, 0x7c, v20
	v_lshl_add_u64 v[40:41], v[24:25], 0, v[40:41]
	v_lshl_add_u64 v[44:45], v[22:23], 0, v[44:45]
	v_ashrrev_i32_e32 v53, 31, v52
	global_load_dword v38, v[38:39], off nt
	v_lshlrev_b64 v[48:49], 15, v[52:53]
	global_load_dword v40, v[40:41], off nt
	s_nop 0
	global_load_dword v41, v[44:45], off offset:1024 nt
	global_load_dword v43, v[44:45], off offset:1536 nt
	v_mad_i64_i32 v[44:45], s[34:35], v46, s25, v[16:17]
	v_lshlrev_b64 v[46:47], 13, v[46:47]
	v_mad_i64_i32 v[54:55], s[34:35], v52, s25, v[16:17]
	v_lshlrev_b64 v[52:53], 13, v[52:53]
	v_lshl_add_u64 v[46:47], v[24:25], 0, v[46:47]
	v_lshl_add_u64 v[50:51], v[22:23], 0, v[48:49]
	v_lshl_add_u64 v[52:53], v[24:25], 0, v[52:53]
	global_load_dword v45, v[44:45], off nt
	v_lshl_add_u64 v[26:27], v[12:13], 0, v[26:27]
	global_load_dword v47, v[46:47], off nt
	s_nop 0
	global_load_dword v48, v[50:51], off offset:1024 nt
	s_nop 0
	global_load_dword v50, v[50:51], off offset:1536 nt
	s_mov_b32 s9, 0
	global_load_dword v39, v[54:55], off nt
	global_load_dword v51, v[52:53], off nt
	s_waitcnt vmcnt(15)
	v_mov_b32_e32 v44, v2
	s_waitcnt vmcnt(14)
	v_mov_b32_e32 v46, v21
	s_waitcnt vmcnt(13)
	v_mov_b32_e32 v49, v28
	s_waitcnt vmcnt(12)
	v_mov_b32_e32 v52, v29
	s_waitcnt vmcnt(11)
	v_mov_b32_e32 v53, v36
	s_waitcnt vmcnt(10)
	v_mov_b32_e32 v54, v37
	s_waitcnt vmcnt(9)
	v_mov_b32_e32 v55, v38
	s_waitcnt vmcnt(8)
	v_mov_b32_e32 v56, v40
	s_waitcnt vmcnt(7)
	v_mov_b32_e32 v57, v41
	s_waitcnt vmcnt(6)
	v_mov_b32_e32 v58, v43
	s_waitcnt vmcnt(5)
	v_mov_b32_e32 v59, v45
	s_waitcnt vmcnt(4)
	v_mov_b32_e32 v60, v47
	s_waitcnt vmcnt(3)
	v_mov_b32_e32 v61, v48
	s_waitcnt vmcnt(2)
	v_mov_b32_e32 v62, v50
	s_waitcnt vmcnt(1)
	v_mov_b32_e32 v63, v39
	s_waitcnt vmcnt(0)
	v_mov_b32_e32 v64, v51
	s_branch .LBB0_562

; #define P6R_LOAD(W, g_) _Pragma("unroll") for (int s_ = 0; s_ < 4; ++s_) { const size_t tr_ = (size_t)(t0 + CHUNK - 1 - 4 * (g_) - s_); W[s_][0] = *(const unsigned*)(gp + tr_ * NG + 512); W[s_][1] = *(const unsigned*)(gp + tr_ * NG + 768); \
;                     W[s_][2] = *(const unsigned*)(yp + tr_ * NZ); W[s_][3] = *(const unsigned*)(ap + tr_ * D); }
; __global__ void __launch_bounds__(NWAVES * 64, 2) fwd(Args args) {
;     ...
;                   P6R_LOAD(wn, 0);
; #pragma unroll 1
;                   for (int g4 = 0; g4 < CHUNK / 4; ++g4) {
; #pragma unroll
;                     for (int s_ = 0; s_ < 4; ++s_)
; #pragma unroll
;                         for (int q_ = 0; q_ < 4; ++q_) wc_[s_][q_] = wn[s_][q_];
;                     if (g4 + 1 < CHUNK / 4) { P6R_LOAD(wn, g4 + 1); }
.LBB0_562:
	s_cmpk_lg_i32 s9, 0xff84
	s_cbranch_scc0 .LBB0_561
	v_add_u32_e32 v64, s9, v20
	v_add_u32_e32 v52, 0x7b, v64
	v_ashrrev_i32_e32 v53, 31, v52
	v_lshlrev_b64 v[54:55], 15, v[52:53]
	v_lshl_add_u64 v[54:55], v[22:23], 0, v[54:55]
	global_load_dword v44, v[54:55], off offset:1024 nt
	global_load_dword v46, v[54:55], off offset:1536 nt
	v_mad_i64_i32 v[54:55], s[34:35], v52, s25, v[16:17]
	v_lshlrev_b64 v[52:53], 13, v[52:53]
	v_add_u32_e32 v56, 0x7a, v64
	v_lshl_add_u64 v[52:53], v[24:25], 0, v[52:53]
	v_ashrrev_i32_e32 v57, 31, v56
	global_load_dword v49, v[54:55], off nt
	v_mad_i64_i32 v[58:59], s[34:35], v56, s25, v[16:17]
	global_load_dword v52, v[52:53], off nt
	v_lshlrev_b64 v[54:55], 15, v[56:57]
	v_lshlrev_b64 v[56:57], 13, v[56:57]
	v_add_u32_e32 v60, 0x79, v64
	v_lshl_add_u64 v[54:55], v[22:23], 0, v[54:55]
	v_lshl_add_u64 v[56:57], v[24:25], 0, v[56:57]
	v_ashrrev_i32_e32 v61, 31, v60
	global_load_dword v53, v[54:55], off offset:1024 nt
	s_nop 0
	global_load_dword v54, v[54:55], off offset:1536 nt
	v_mad_i64_i32 v[62:63], s[34:35], v60, s25, v[16:17]
	global_load_dword v55, v[58:59], off nt
	v_add_u32_e32 v64, 0x78, v64
	global_load_dword v56, v[56:57], off nt
	v_lshlrev_b64 v[58:59], 15, v[60:61]
	v_lshlrev_b64 v[60:61], 13, v[60:61]
	v_lshl_add_u64 v[58:59], v[22:23], 0, v[58:59]
	v_lshl_add_u64 v[60:61], v[24:25], 0, v[60:61]
	v_ashrrev_i32_e32 v65, 31, v64
	global_load_dword v57, v[58:59], off offset:1024 nt
	s_nop 0
	global_load_dword v58, v[58:59], off offset:1536 nt
	v_mad_i64_i32 v[66:67], s[34:35], v64, s25, v[16:17]
	global_load_dword v59, v[62:63], off nt
	s_nop 0
	global_load_dword v60, v[60:61], off nt
	v_lshlrev_b64 v[62:63], 15, v[64:65]
	v_lshlrev_b64 v[64:65], 13, v[64:65]
	v_lshl_add_u64 v[62:63], v[22:23], 0, v[62:63]
	v_lshl_add_u64 v[64:65], v[24:25], 0, v[64:65]
	global_load_dword v61, v[62:63], off offset:1024 nt
	s_nop 0
	global_load_dword v62, v[62:63], off offset:1536 nt
	s_nop 0
	global_load_dword v63, v[66:67], off nt
	s_nop 0
	global_load_dword v64, v[64:65], off nt
	s_branch .LBB0_561
